# row passes: 64-lane sums via DPP prefix reduction (row_shr/row_bcast + readlane) instead of six ds_bpermute butterfly steps each behind lgkmcnt(0)
# baseline (speedup 1.0000x reference)
; DEVI unsigned pk_bf16(float lo, float hi) { unsigned r; asm("v_cvt_pk_bf16_f32 %0, %1, %2" : "=v"(r) : "v"(lo), "v"(hi)); return r; }
; DEVI float wave_sum(float v) { for (int o = 32; o; o >>= 1) v += __shfl_xor(v, o); return v; }
; __device__ __forceinline__ void norm_phase(const Params& p, const float* __restrict__ gain, int mode, int nslab) {
;     ...
;     float ss = 0.f;
; #pragma unroll
;     for (int i = 0; i < 4; ++i) ss += v[i].x * v[i].x + v[i].y * v[i].y + v[i].z * v[i].z + v[i].w * v[i].w;
;     ss = wave_sum(ss);
;     const float rs = rsqrtf(ss * (1.0f / 1024.0f) + EPS);
; #pragma unroll
;     for (int i = 0; i < 4; ++i) {
;       const float4 g = *(const float4*)(gain + i * 256 + lane * 4);
;       uint2 w; w.x = pk_bf16(v[i].x * rs * g.x, v[i].y * rs * g.y); w.y = pk_bf16(v[i].z * rs * g.z, v[i].w * rs * g.w);
;       *(uint2*)(xn + (size_t)r * 1024 + i * 256 + lane * 4) = w;
;     }
.LBB0_145:
	s_or_b64 exec, exec, s[8:9]
	v_mov_b32_e32 v54, v10
	v_mov_b32_e32 v55, v14
	v_pk_mul_f32 v[54:55], v[54:55], v[54:55]
	v_mov_b32_e32 v56, v11
	v_mov_b32_e32 v57, v15
	v_pk_fma_f32 v[54:55], v[56:57], v[56:57], v[54:55]
	v_mov_b32_e32 v56, v12
	v_mov_b32_e32 v57, v16
	v_pk_fma_f32 v[54:55], v[56:57], v[56:57], v[54:55]
	v_mov_b32_e32 v56, v13
	v_mov_b32_e32 v57, v17
	v_pk_fma_f32 v[62:63], v[56:57], v[56:57], v[54:55]
	v_mov_b32_e32 v54, v2
	v_mov_b32_e32 v55, v6
	v_pk_mul_f32 v[58:59], v[54:55], v[54:55]
	v_mov_b32_e32 v60, v3
	v_mov_b32_e32 v61, v7
	v_pk_fma_f32 v[64:65], v[60:61], v[60:61], v[58:59]
	v_mov_b32_e32 v66, v4
	v_mov_b32_e32 v67, v8
	v_pk_fma_f32 v[64:65], v[66:67], v[66:67], v[64:65]
	v_mov_b32_e32 v66, v5
	v_mov_b32_e32 v67, v9
	v_pk_fma_f32 v[64:65], v[66:67], v[66:67], v[64:65]
	v_add_f32_e32 v39, v62, v63
	v_add_f32_e32 v39, v65, v39
	v_add_f32_e32 v39, v64, v39
	global_load_dwordx4 v[62:65], v[42:43], off offset:3072
	global_load_dwordx4 v[54:57], v[42:43], off offset:1024
	global_load_dwordx4 v[58:61], v[42:43], off offset:2048
	s_and_b64 s[0:1], exec, vcc
	s_or_b64 s[6:7], s[0:1], s[6:7]
	s_nop 1
	v_add_f32_dpp v39, v39, v39 row_shr:1 row_mask:0xf bank_mask:0xf
	s_nop 1
	v_add_f32_dpp v39, v39, v39 row_shr:2 row_mask:0xf bank_mask:0xf
	s_nop 1
	v_add_f32_dpp v39, v39, v39 row_shr:4 row_mask:0xf bank_mask:0xf
	s_nop 1
	v_add_f32_dpp v39, v39, v39 row_shr:8 row_mask:0xf bank_mask:0xf
	s_nop 1
	v_add_f32_dpp v39, v39, v39 row_bcast:15 row_mask:0xa bank_mask:0xf
	s_nop 1
	v_add_f32_dpp v39, v39, v39 row_bcast:31 row_mask:0xc bank_mask:0xf
	s_nop 0
	v_readlane_b32 s98, v39, 63
	s_nop 1
	v_mov_b32_e32 v39, s98
	v_fmamk_f32 v39, v39, 0x3a800000, v51
	v_mul_f32_e32 v53, 0x4b800000, v39
	v_cmp_gt_f32_e32 vcc, s14, v39
	s_nop 1
	v_cndmask_b32_e32 v39, v39, v53, vcc
	v_rsq_f32_e32 v53, v39
	v_ashrrev_i32_e32 v39, 31, v38
	v_lshlrev_b64 v[38:39], 11, v[38:39]
	v_lshl_add_u64 v[38:39], v[44:45], 0, v[38:39]
	v_mul_f32_e32 v66, 0x45800000, v53
	v_cndmask_b32_e32 v53, v53, v66, vcc
	v_mul_f32_e32 v14, v14, v53
	v_mul_f32_e32 v15, v15, v53
	v_mul_f32_e32 v2, v2, v53
	v_mul_f32_e32 v3, v3, v53
	v_mul_f32_e32 v16, v16, v53
	v_mul_f32_e32 v17, v17, v53
	v_mul_f32_e32 v66, v6, v53
	v_mul_f32_e32 v67, v7, v53
	s_waitcnt vmcnt(3)
	v_mul_f32_e32 v6, v18, v14
	v_mul_f32_e32 v7, v19, v15
	v_mul_f32_e32 v10, v10, v53
	v_mul_f32_e32 v11, v11, v53
	v_mul_f32_e32 v9, v9, v53
	v_mul_f32_e32 v14, v20, v16
	v_mul_f32_e32 v15, v21, v17
	v_cvt_pk_bf16_f32 v6, v6, v7
	v_cvt_pk_bf16_f32 v7, v14, v15
	v_mul_f32_e32 v12, v12, v53
	v_mul_f32_e32 v13, v13, v53
	v_mul_f32_e32 v8, v8, v53
	global_store_dwordx2 v[38:39], v[6:7], off
	v_mov_b64_e32 v[16:17], v[24:25]
	s_waitcnt vmcnt(3)
	v_mul_f32_e32 v2, v2, v62
	v_mul_f32_e32 v3, v3, v63
	v_cvt_pk_bf16_f32 v2, v2, v3
	v_mul_f32_e32 v3, v4, v53
	s_waitcnt vmcnt(2)
	v_mul_f32_e32 v6, v54, v10
	v_mul_f32_e32 v7, v55, v11
	s_waitcnt vmcnt(1)
	v_mul_f32_e32 v9, v9, v61
	v_mul_f32_e32 v3, v3, v64
	v_mul_f32_e32 v4, v5, v53
	v_mul_f32_e32 v10, v56, v12
	v_mul_f32_e32 v11, v57, v13
	v_mul_f32_e32 v12, v66, v58
	v_mul_f32_e32 v13, v67, v59
	v_mul_f32_e32 v14, v8, v60
	v_cvt_pk_bf16_f32 v6, v6, v7
	v_cvt_pk_bf16_f32 v7, v10, v11
	v_cvt_pk_bf16_f32 v8, v12, v13
	v_cvt_pk_bf16_f32 v9, v14, v9
	v_mul_f32_e32 v4, v4, v65
	v_cvt_pk_bf16_f32 v3, v3, v4
	global_store_dwordx2 v[38:39], v[6:7], off offset:512
	global_store_dwordx2 v[38:39], v[8:9], off offset:1024
	global_store_dwordx2 v[38:39], v[2:3], off offset:1536
	v_mov_b32_e32 v38, v52
	v_mov_b64_e32 v[4:5], v[36:37]
	v_mov_b64_e32 v[2:3], v[34:35]
	v_mov_b64_e32 v[8:9], v[32:33]
	v_mov_b64_e32 v[6:7], v[30:31]
	v_mov_b64_e32 v[12:13], v[28:29]
	v_mov_b64_e32 v[10:11], v[26:27]
	v_mov_b64_e32 v[14:15], v[22:23]
	s_andn2_b64 exec, exec, s[6:7]
	s_cbranch_execz .LBB0_151

; DEVI unsigned pk_bf16(float lo, float hi) { unsigned r; asm("v_cvt_pk_bf16_f32 %0, %1, %2" : "=v"(r) : "v"(lo), "v"(hi)); return r; }
; DEVI float wave_sum(float v) { for (int o = 32; o; o >>= 1) v += __shfl_xor(v, o); return v; }
; __device__ __forceinline__ void norm_phase(const Params& p, const float* __restrict__ gain, int mode, int nslab) {
;     ...
;     float ss = 0.f;
; #pragma unroll
;     for (int i = 0; i < 4; ++i) ss += v[i].x * v[i].x + v[i].y * v[i].y + v[i].z * v[i].z + v[i].w * v[i].w;
;     ss = wave_sum(ss);
;     const float rs = rsqrtf(ss * (1.0f / 1024.0f) + EPS);
; #pragma unroll
;     for (int i = 0; i < 4; ++i) {
;       const float4 g = *(const float4*)(gain + i * 256 + lane * 4);
;       uint2 w; w.x = pk_bf16(v[i].x * rs * g.x, v[i].y * rs * g.y); w.y = pk_bf16(v[i].z * rs * g.z, v[i].w * rs * g.w);
;       *(uint2*)(xn + (size_t)r * 1024 + i * 256 + lane * 4) = w;
;     }
.LBB0_1019:
	s_or_b64 exec, exec, s[0:1]
	v_mov_b32_e32 v48, v28
	v_mov_b32_e32 v49, v32
	v_pk_mul_f32 v[48:49], v[48:49], v[48:49]
	v_mov_b32_e32 v50, v29
	v_mov_b32_e32 v51, v33
	v_pk_fma_f32 v[48:49], v[50:51], v[50:51], v[48:49]
	v_mov_b32_e32 v50, v30
	v_mov_b32_e32 v51, v34
	v_pk_fma_f32 v[48:49], v[50:51], v[50:51], v[48:49]
	v_mov_b32_e32 v50, v31
	v_mov_b32_e32 v51, v35
	v_pk_fma_f32 v[48:49], v[50:51], v[50:51], v[48:49]
	v_mov_b32_e32 v50, v20
	v_mov_b32_e32 v51, v24
	v_pk_mul_f32 v[50:51], v[50:51], v[50:51]
	v_mov_b32_e32 v52, v21
	v_mov_b32_e32 v53, v25
	v_pk_fma_f32 v[50:51], v[52:53], v[52:53], v[50:51]
	v_mov_b32_e32 v52, v22
	v_mov_b32_e32 v53, v26
	v_pk_fma_f32 v[50:51], v[52:53], v[52:53], v[50:51]
	v_mov_b32_e32 v52, v23
	v_mov_b32_e32 v53, v27
	v_pk_fma_f32 v[50:51], v[52:53], v[52:53], v[50:51]
	v_add_f32_e32 v43, v48, v49
	v_add_f32_e32 v43, v51, v43
	v_add_f32_e32 v43, v50, v43
	v_ashrrev_i32_e32 v47, 31, v46
	v_lshlrev_b64 v[46:47], 11, v[46:47]
	v_lshl_add_u64 v[46:47], v[38:39], 0, v[46:47]
	v_add_u32_e32 v42, s80, v42
	s_nop 1
	v_add_f32_dpp v43, v43, v43 row_shr:1 row_mask:0xf bank_mask:0xf
	s_nop 1
	v_add_f32_dpp v43, v43, v43 row_shr:2 row_mask:0xf bank_mask:0xf
	s_nop 1
	v_add_f32_dpp v43, v43, v43 row_shr:4 row_mask:0xf bank_mask:0xf
	s_nop 1
	v_add_f32_dpp v43, v43, v43 row_shr:8 row_mask:0xf bank_mask:0xf
	s_nop 1
	v_add_f32_dpp v43, v43, v43 row_bcast:15 row_mask:0xa bank_mask:0xf
	s_nop 1
	v_add_f32_dpp v43, v43, v43 row_bcast:31 row_mask:0xc bank_mask:0xf
	s_nop 0
	v_readlane_b32 s98, v43, 63
	s_nop 1
	v_mov_b32_e32 v43, s98
	v_fmamk_f32 v43, v43, 0x3a800000, v132
	v_cmp_gt_f32_e32 vcc, s82, v43
	v_mul_f32_e32 v45, 0x4b800000, v43
	s_nop 0
	v_cndmask_b32_e32 v43, v43, v45, vcc
	v_rsq_f32_e32 v43, v43
	s_nop 0
	v_mul_f32_e32 v45, 0x45800000, v43
	v_cndmask_b32_e32 v43, v43, v45, vcc
	v_mul_f32_e32 v32, v32, v43
	v_mul_f32_e32 v33, v33, v43
	s_waitcnt vmcnt(0)
	v_mul_f32_e32 v32, v0, v32
	v_mul_f32_e32 v33, v1, v33
	v_cvt_pk_bf16_f32 v32, v32, v33
	v_mul_f32_e32 v33, v34, v43
	v_mul_f32_e32 v33, v2, v33
	v_mul_f32_e32 v34, v35, v43
	v_mul_f32_e32 v34, v3, v34
	v_cvt_pk_bf16_f32 v33, v33, v34
	global_store_dwordx2 v[46:47], v[32:33], off
	v_mul_f32_e32 v28, v28, v43
	v_mul_f32_e32 v29, v29, v43
	v_mul_f32_e32 v24, v24, v43
	v_mul_f32_e32 v25, v25, v43
	v_mul_f32_e32 v20, v20, v43
	v_mul_f32_e32 v21, v21, v43
	v_mov_b64_e32 v[32:33], v[112:113]
	v_mov_b64_e32 v[34:35], v[114:115]
	v_mul_f32_e32 v28, v32, v28
	v_mul_f32_e32 v29, v33, v29
	v_cvt_pk_bf16_f32 v28, v28, v29
	v_mul_f32_e32 v29, v30, v43
	v_mul_f32_e32 v29, v34, v29
	v_mul_f32_e32 v30, v31, v43
	v_mul_f32_e32 v30, v35, v30
	v_cvt_pk_bf16_f32 v29, v29, v30
	global_store_dwordx2 v[46:47], v[28:29], off offset:512
	v_mov_b64_e32 v[34:35], v[6:7]
	v_mov_b64_e32 v[32:33], v[4:5]
	v_mov_b64_e32 v[28:29], v[116:117]
	v_mov_b64_e32 v[30:31], v[118:119]
	v_mul_f32_e32 v24, v28, v24
	v_mul_f32_e32 v25, v29, v25
	v_cvt_pk_bf16_f32 v24, v24, v25
	v_mul_f32_e32 v25, v26, v43
	v_mul_f32_e32 v25, v30, v25
	v_mul_f32_e32 v26, v27, v43
	v_mul_f32_e32 v26, v26, v31
	v_cvt_pk_bf16_f32 v25, v25, v26
	global_store_dwordx2 v[46:47], v[24:25], off offset:1024
	v_mov_b64_e32 v[30:31], v[10:11]
	v_mov_b64_e32 v[28:29], v[8:9]
	v_mov_b64_e32 v[24:25], v[120:121]
	v_mov_b64_e32 v[26:27], v[122:123]
	v_mul_f32_e32 v20, v20, v24
	v_mul_f32_e32 v21, v21, v25
	v_cvt_pk_bf16_f32 v20, v20, v21
	v_mul_f32_e32 v21, v22, v43
	v_mul_f32_e32 v21, v21, v26
	v_mul_f32_e32 v22, v23, v43
	v_mul_f32_e32 v22, v22, v27
	v_cvt_pk_bf16_f32 v21, v21, v22
	global_store_dwordx2 v[46:47], v[20:21], off offset:1536
	v_mov_b32_e32 v46, v62
	v_mov_b64_e32 v[22:23], v[18:19]
	v_mov_b64_e32 v[20:21], v[16:17]
	v_mov_b64_e32 v[26:27], v[14:15]
	v_mov_b64_e32 v[24:25], v[12:13]
	s_andn2_b64 exec, exec, s[4:5]
	s_cbranch_execz .LBB0_1034

; DEVI unsigned pk_bf16(float lo, float hi) { unsigned r; asm("v_cvt_pk_bf16_f32 %0, %1, %2" : "=v"(r) : "v"(lo), "v"(hi)); return r; }
; DEVI float bf_lo(unsigned u) { return __uint_as_float(u << 16); }
; DEVI float bf_hi(unsigned u) { return __uint_as_float(u & 0xffff0000u); }
; DEVI float wave_sum(float v) { for (int o = 32; o; o >>= 1) v += __shfl_xor(v, o); return v; }
; __device__ __forceinline__ void oddprep_phase(const Params& p) {
;     ...
;     {
;       unsigned u[3]; float ss = 0.f;
; #pragma unroll
;       for (int j = 0; j < 3; ++j) { u[j] = *(const unsigned*)(zr + 128 * j + 2 * lane); ss += bf_lo(u[j]) * bf_lo(u[j]) + bf_hi(u[j]) * bf_hi(u[j]); }
;       ss = wave_sum(ss); const float rs = rsqrtf(ss * (1.0f / 384.0f) + EPS);
; #pragma unroll
;       for (int j = 0; j < 3; ++j) { const float* gp = p.od_g_qa + 128 * j + 2 * lane; *(unsigned*)(zr + 128 * j + 2 * lane) = pk_bf16(bf_lo(u[j]) * rs * gp[0], bf_hi(u[j]) * rs * gp[1]); }
;     }
;     {
;       const uint2 u = *(const uint2*)(zr + 384 + 4 * lane);
;       float v0 = bf_lo(u.x), v1 = bf_hi(u.x), v2 = bf_lo(u.y), v3 = bf_hi(u.y);
;       float ss = wave_sum(v0 * v0 + v1 * v1 + v2 * v2 + v3 * v3); const float rs = rsqrtf(ss * (1.0f / 256.0f) + EPS);
;       const float* gp = p.od_g_kva + 4 * lane; uint2 o; o.x = pk_bf16(v0 * rs * gp[0], v1 * rs * gp[1]); o.y = pk_bf16(v2 * rs * gp[2], v3 * rs * gp[3]);
;       *(uint2*)(zr + 384 + 4 * lane) = o;
;     }
;     {
;       const int b = r / T, t = r - b * T;
;       const int pos = t < 16 ? t : p.pos[b * 4096 + (t - 16)] + 16;
.LBB0_1263:
	v_readlane_b32 s16, v253, 2
	v_readlane_b32 s18, v253, 4
	v_readlane_b32 s19, v253, 5
	s_mov_b32 s10, 0x7895000
	v_readlane_b32 s17, v253, 3
	v_lshl_add_u64 v[0:1], s[18:19], 0, v[26:27]
	v_add_co_u32_e32 v0, vcc, 0x7895000, v0
	s_nop 1
	v_addc_co_u32_e32 v1, vcc, 0, v1, vcc
	global_load_dword v5, v[0:1], off offset:2304
	global_load_dword v3, v[0:1], off offset:2560
	global_load_dword v36, v[0:1], off offset:2816
	v_lshl_add_u64 v[92:93], s[18:19], 0, v[30:31]
	v_add_co_u32_e32 v92, vcc, 0x7895000, v92
	s_nop 1
	v_addc_co_u32_e32 v93, vcc, 0, v93, vcc
	global_load_dwordx4 v[96:99], v[92:93], off offset:3648
	v_add_co_u32_e32 v94, vcc, 0x1000, v92
	s_nop 1
	v_addc_co_u32_e32 v95, vcc, 0, v93, vcc
	global_load_dwordx4 v[100:103], v[94:95], off offset:576
	v_lshl_add_u64 v[94:95], s[18:19], 0, v[24:25]
	v_add_co_u32_e32 v94, vcc, 0x7895000, v94
	s_nop 1
	v_addc_co_u32_e32 v95, vcc, 0, v95, vcc
	global_load_dwordx2 v[104:105], v[94:95], off offset:3072
	s_mov_b64 s[100:101], exec
	s_and_b64 exec, exec, s[2:3]
	v_lshl_add_u64 v[106:107], s[18:19], 0, v[28:29]
	global_load_ushort v108, v[106:107], off
	s_mov_b64 exec, s[100:101]
	s_and_b64 exec, exec, s[6:7]
	v_lshl_add_u64 v[106:107], s[18:19], 0, v[22:23]
	global_load_dword v109, v[106:107], off
	s_mov_b64 exec, s[100:101]
	v_mul_hi_i32 v111, v4, s23
	v_lshrrev_b32_e32 v112, 31, v111
	v_ashrrev_i32_e32 v111, 11, v111
	v_add_u32_e32 v112, v111, v112
	v_readlane_b32 s98, v253, 30
	v_readlane_b32 s99, v253, 31
	v_mul_i32_i24_e32 v111, 0xffffeff0, v112
	v_lshl_add_u32 v111, v112, 12, v111
	v_add3_u32 v112, v4, v111, -16
	v_max_i32_e32 v112, 0, v112
	v_mov_b32_e32 v113, 0
	v_lshl_add_u64 v[112:113], v[112:113], 2, s[98:99]
	global_load_dword v114, v[112:113], off
	s_waitcnt vmcnt(8)
	v_lshlrev_b32_e32 v34, 16, v5
	s_waitcnt vmcnt(7)
	v_lshlrev_b32_e32 v2, 16, v3
	v_and_b32_e32 v3, 0xffff0000, v3
	s_waitcnt vmcnt(6)
	v_lshlrev_b32_e32 v35, 16, v36
	v_and_b32_e32 v37, 0xffff0000, v36
	v_and_b32_e32 v36, 0xffff0000, v5
	v_pk_mul_f32 v[32:33], v[2:3], v[2:3]
	v_pk_mul_f32 v[46:47], v[36:37], v[36:37]
	v_add_f32_e32 v5, v32, v33
	v_pk_fma_f32 v[46:47], v[34:35], v[34:35], v[46:47]
	s_nop 0
	v_add_f32_e32 v5, v46, v5
	v_add_f32_e32 v5, v5, v47
	s_nop 1
	v_add_f32_dpp v5, v5, v5 row_shr:1 row_mask:0xf bank_mask:0xf
	s_nop 1
	v_add_f32_dpp v5, v5, v5 row_shr:2 row_mask:0xf bank_mask:0xf
	s_nop 1
	v_add_f32_dpp v5, v5, v5 row_shr:4 row_mask:0xf bank_mask:0xf
	s_nop 1
	v_add_f32_dpp v5, v5, v5 row_shr:8 row_mask:0xf bank_mask:0xf
	s_nop 1
	v_add_f32_dpp v5, v5, v5 row_bcast:15 row_mask:0xa bank_mask:0xf
	s_nop 1
	v_add_f32_dpp v5, v5, v5 row_bcast:31 row_mask:0xc bank_mask:0xf
	s_nop 0
	v_readlane_b32 s98, v5, 63
	s_nop 1
	v_mov_b32_e32 v5, s98
	v_fmamk_f32 v5, v5, 0x3b2aaaab, v132
	v_cmp_gt_f32_e32 vcc, s81, v5
	v_mul_f32_e32 v32, 0x4b800000, v5
	s_nop 0
	v_cndmask_b32_e32 v5, v5, v32, vcc
	v_rsq_f32_e32 v5, v5
	s_nop 0
	v_mul_f32_e32 v32, 0x45800000, v5
	v_cndmask_b32_e32 v5, v5, v32, vcc
	v_mul_f32_e32 v34, v5, v34
	v_mul_f32_e32 v2, v5, v2
	v_mul_f32_e32 v3, v5, v3
	s_nop 1
	v_mov_b64_e32 v[32:33], v[64:65]
	v_mul_f32_e32 v32, v32, v34
	v_mul_f32_e32 v34, v5, v36
	v_mul_f32_e32 v33, v33, v34
	v_cvt_pk_bf16_f32 v32, v32, v33
	global_store_dword v[0:1], v32, off offset:2304
	s_nop 1
	v_mov_b64_e32 v[32:33], v[66:67]
	v_mul_f32_e32 v2, v32, v2
	v_mul_f32_e32 v3, v33, v3
	v_cvt_pk_bf16_f32 v2, v2, v3
	global_store_dword v[0:1], v2, off offset:2560
	v_mul_f32_e32 v32, v5, v35
	v_mul_f32_e32 v5, v5, v37
	s_nop 1
	v_mov_b64_e32 v[2:3], v[68:69]
	v_mul_f32_e32 v2, v2, v32
	v_mul_f32_e32 v3, v3, v5
	v_cvt_pk_bf16_f32 v2, v2, v3
	global_store_dword v[0:1], v2, off offset:2816
	v_lshl_add_u64 v[0:1], s[18:19], 0, v[24:25]
	v_add_co_u32_e32 v32, vcc, s10, v0
	s_nop 1
	v_addc_co_u32_e32 v33, vcc, 0, v1, vcc
	s_waitcnt vmcnt(0)
	v_mov_b64_e32 v[0:1], v[104:105]
	v_lshlrev_b32_e32 v34, 16, v0
	v_and_b32_e32 v35, 0xffff0000, v0
	v_lshlrev_b32_e32 v37, 16, v1
	v_and_b32_e32 v36, 0xffff0000, v1
	v_pk_mul_f32 v[0:1], v[34:35], v[34:35]
	v_pk_mul_f32 v[2:3], v[36:37], v[36:37]
	v_add_f32_e32 v0, v0, v1
	v_add_f32_e32 v0, v0, v3
	v_add_f32_e32 v0, v2, v0
	s_nop 1
	v_add_f32_dpp v0, v0, v0 row_shr:1 row_mask:0xf bank_mask:0xf
	s_nop 1
	v_add_f32_dpp v0, v0, v0 row_shr:2 row_mask:0xf bank_mask:0xf
	s_nop 1
	v_add_f32_dpp v0, v0, v0 row_shr:4 row_mask:0xf bank_mask:0xf
	s_nop 1
	v_add_f32_dpp v0, v0, v0 row_shr:8 row_mask:0xf bank_mask:0xf
	s_nop 1
	v_add_f32_dpp v0, v0, v0 row_bcast:15 row_mask:0xa bank_mask:0xf
	s_nop 1
	v_add_f32_dpp v0, v0, v0 row_bcast:31 row_mask:0xc bank_mask:0xf
	s_nop 0
	v_readlane_b32 s98, v0, 63
	s_nop 1
	v_mov_b32_e32 v0, s98
	v_fmamk_f32 v0, v0, 0x3b800000, v132
	v_cmp_gt_f32_e32 vcc, s81, v0
	v_mul_f32_e32 v1, 0x4b800000, v0
	s_nop 0
	v_cndmask_b32_e32 v0, v0, v1, vcc
	v_rsq_f32_e32 v0, v0
	s_nop 0
	v_mul_f32_e32 v1, 0x45800000, v0
	v_cndmask_b32_e32 v5, v0, v1, vcc
	v_mul_f32_e32 v34, v5, v34
	s_nop 1
	v_mov_b64_e32 v[0:1], v[72:73]
	v_mov_b64_e32 v[2:3], v[74:75]
	v_mul_f32_e32 v0, v0, v34
	v_mul_f32_e32 v34, v5, v35
	v_mul_f32_e32 v1, v1, v34
	v_cvt_pk_bf16_f32 v0, v0, v1
	v_mul_f32_e32 v1, v5, v37
	v_mul_f32_e32 v1, v2, v1
	v_mul_f32_e32 v2, v5, v36
	v_mul_f32_e32 v2, v3, v2
	v_cvt_pk_bf16_f32 v1, v1, v2
	global_store_dwordx2 v[32:33], v[0:1], off offset:3072
	v_mul_hi_i32 v0, v4, s23
	v_lshrrev_b32_e32 v1, 31, v0
	v_ashrrev_i32_e32 v0, 11, v0
	v_add_u32_e32 v1, v0, v1
	v_mad_i32_i24 v0, v1, s24, v4
	v_cmp_lt_i32_e32 vcc, 15, v0
	s_and_saveexec_b64 s[10:11], vcc
	s_cbranch_execz .LBB0_1265
	v_mul_i32_i24_e32 v0, 0xffffeff0, v1
	v_lshl_add_u32 v0, v1, 12, v0
	v_add3_u32 v0, v4, v0, -16
	v_readlane_b32 s36, v253, 28
	v_ashrrev_i32_e32 v1, 31, v0
	v_readlane_b32 s38, v253, 30
	v_readlane_b32 s39, v253, 31
	v_readlane_b32 s37, v253, 29
	v_readlane_b32 s40, v253, 32
	v_lshl_add_u64 v[0:1], v[0:1], 2, s[38:39]
	v_readlane_b32 s41, v253, 33
	v_readlane_b32 s42, v253, 34
	v_readlane_b32 s43, v253, 35
	v_readlane_b32 s44, v253, 36
	v_readlane_b32 s45, v253, 37
	v_readlane_b32 s46, v253, 38
	v_readlane_b32 s47, v253, 39
	v_readlane_b32 s48, v253, 40
	v_readlane_b32 s49, v253, 41
	v_readlane_b32 s50, v253, 42
	v_readlane_b32 s51, v253, 43
	s_waitcnt vmcnt(0)
	v_mov_b32_e32 v0, v114
	v_add_u32_e32 v0, 16, v0

; DEVI unsigned pk_bf16(float lo, float hi) { unsigned r; asm("v_cvt_pk_bf16_f32 %0, %1, %2" : "=v"(r) : "v"(lo), "v"(hi)); return r; }
; DEVI float wave_sum(float v) { for (int o = 32; o; o >>= 1) v += __shfl_xor(v, o); return v; }
; __device__ __forceinline__ void norm_phase(const Params& p, const float* __restrict__ gain, int mode, int nslab) {
;     ...
;     float ss = 0.f;
; #pragma unroll
;     for (int i = 0; i < 4; ++i) ss += v[i].x * v[i].x + v[i].y * v[i].y + v[i].z * v[i].z + v[i].w * v[i].w;
;     ss = wave_sum(ss);
;     const float rs = rsqrtf(ss * (1.0f / 1024.0f) + EPS);
; #pragma unroll
;     for (int i = 0; i < 4; ++i) {
;       const float4 g = *(const float4*)(gain + i * 256 + lane * 4);
;       uint2 w; w.x = pk_bf16(v[i].x * rs * g.x, v[i].y * rs * g.y); w.y = pk_bf16(v[i].z * rs * g.z, v[i].w * rs * g.w);
;       *(uint2*)(xn + (size_t)r * 1024 + i * 256 + lane * 4) = w;
;     }
.LBB0_2091:
	s_or_b64 exec, exec, s[0:1]
	v_mov_b32_e32 v48, v28
	v_mov_b32_e32 v49, v32
	v_pk_mul_f32 v[48:49], v[48:49], v[48:49]
	v_mov_b32_e32 v50, v29
	v_mov_b32_e32 v51, v33
	v_pk_fma_f32 v[48:49], v[50:51], v[50:51], v[48:49]
	v_mov_b32_e32 v50, v30
	v_mov_b32_e32 v51, v34
	v_pk_fma_f32 v[48:49], v[50:51], v[50:51], v[48:49]
	v_mov_b32_e32 v50, v31
	v_mov_b32_e32 v51, v35
	v_pk_fma_f32 v[48:49], v[50:51], v[50:51], v[48:49]
	v_mov_b32_e32 v50, v0
	v_mov_b32_e32 v51, v8
	v_pk_mul_f32 v[50:51], v[50:51], v[50:51]
	v_mov_b32_e32 v52, v1
	v_mov_b32_e32 v53, v9
	v_pk_fma_f32 v[50:51], v[52:53], v[52:53], v[50:51]
	v_mov_b32_e32 v52, v2
	v_mov_b32_e32 v53, v10
	v_pk_fma_f32 v[50:51], v[52:53], v[52:53], v[50:51]
	v_mov_b32_e32 v52, v3
	v_mov_b32_e32 v53, v11
	v_pk_fma_f32 v[50:51], v[52:53], v[52:53], v[50:51]
	v_add_f32_e32 v45, v48, v49
	v_add_f32_e32 v45, v51, v45
	v_add_f32_e32 v45, v50, v45
	v_add_u32_e32 v44, s80, v44
	s_nop 1
	v_add_f32_dpp v45, v45, v45 row_shr:1 row_mask:0xf bank_mask:0xf
	s_nop 1
	v_add_f32_dpp v45, v45, v45 row_shr:2 row_mask:0xf bank_mask:0xf
	s_nop 1
	v_add_f32_dpp v45, v45, v45 row_shr:4 row_mask:0xf bank_mask:0xf
	s_nop 1
	v_add_f32_dpp v45, v45, v45 row_shr:8 row_mask:0xf bank_mask:0xf
	s_nop 1
	v_add_f32_dpp v45, v45, v45 row_bcast:15 row_mask:0xa bank_mask:0xf
	s_nop 1
	v_add_f32_dpp v45, v45, v45 row_bcast:31 row_mask:0xc bank_mask:0xf
	s_nop 0
	v_readlane_b32 s98, v45, 63
	s_nop 1
	v_mov_b32_e32 v45, s98
	v_fmamk_f32 v45, v45, 0x3a800000, v132
	v_cmp_gt_f32_e32 vcc, s25, v45
	v_mul_f32_e32 v47, 0x4b800000, v45
	s_nop 0
	v_cndmask_b32_e32 v45, v45, v47, vcc
	v_rsq_f32_e32 v45, v45
	s_nop 0
	v_mul_f32_e32 v47, 0x45800000, v45
	v_cndmask_b32_e32 v45, v45, v47, vcc
	v_mul_f32_e32 v32, v32, v45
	v_mul_f32_e32 v33, v33, v45
	s_waitcnt vmcnt(0)
	v_mul_f32_e32 v32, v4, v32
	v_mul_f32_e32 v33, v5, v33
	v_ashrrev_i32_e32 v47, 31, v46
	v_cvt_pk_bf16_f32 v32, v32, v33
	v_mul_f32_e32 v33, v34, v45
	v_lshlrev_b64 v[46:47], 11, v[46:47]
	v_mul_f32_e32 v33, v6, v33
	v_mul_f32_e32 v34, v35, v45
	v_lshl_add_u64 v[46:47], v[40:41], 0, v[46:47]
	v_mul_f32_e32 v34, v7, v34
	v_cvt_pk_bf16_f32 v33, v33, v34
	global_store_dwordx2 v[46:47], v[32:33], off
	v_mul_f32_e32 v28, v28, v45
	v_mul_f32_e32 v29, v29, v45
	v_mul_f32_e32 v8, v8, v45
	v_mul_f32_e32 v9, v9, v45
	v_mul_f32_e32 v0, v0, v45
	v_mul_f32_e32 v1, v1, v45
	v_mov_b64_e32 v[32:33], v[112:113]
	v_mov_b64_e32 v[34:35], v[114:115]
	v_mul_f32_e32 v28, v32, v28
	v_mul_f32_e32 v29, v33, v29
	v_cvt_pk_bf16_f32 v28, v28, v29
	v_mul_f32_e32 v29, v30, v45
	v_mul_f32_e32 v29, v34, v29
	v_mul_f32_e32 v30, v31, v45
	v_mul_f32_e32 v30, v35, v30
	v_cvt_pk_bf16_f32 v29, v29, v30
	global_store_dwordx2 v[46:47], v[28:29], off offset:512
	v_mov_b64_e32 v[34:35], v[14:15]
	v_mov_b64_e32 v[32:33], v[12:13]
	v_mov_b64_e32 v[28:29], v[116:117]
	v_mov_b64_e32 v[30:31], v[118:119]
	v_mul_f32_e32 v8, v28, v8
	v_mul_f32_e32 v9, v29, v9
	v_cvt_pk_bf16_f32 v8, v8, v9
	v_mul_f32_e32 v9, v10, v45
	v_mul_f32_e32 v9, v30, v9
	v_mul_f32_e32 v10, v11, v45
	v_mul_f32_e32 v10, v10, v31
	v_cvt_pk_bf16_f32 v9, v9, v10
	global_store_dwordx2 v[46:47], v[8:9], off offset:1024
	v_mov_b64_e32 v[30:31], v[18:19]
	v_mov_b64_e32 v[28:29], v[16:17]
	v_mov_b64_e32 v[8:9], v[120:121]
	v_mov_b64_e32 v[10:11], v[122:123]
	v_mul_f32_e32 v0, v0, v8
	v_mul_f32_e32 v1, v1, v9
	v_cvt_pk_bf16_f32 v0, v0, v1
	v_mul_f32_e32 v1, v2, v45
	v_mul_f32_e32 v1, v1, v10
	v_mul_f32_e32 v2, v3, v45
	v_mul_f32_e32 v2, v2, v11
	v_cvt_pk_bf16_f32 v1, v1, v2
	global_store_dwordx2 v[46:47], v[0:1], off offset:1536
	v_mov_b32_e32 v46, v59
	v_mov_b64_e32 v[2:3], v[26:27]
	v_mov_b64_e32 v[0:1], v[24:25]
	v_mov_b64_e32 v[10:11], v[22:23]
	v_mov_b64_e32 v[8:9], v[20:21]
	s_andn2_b64 exec, exec, s[4:5]
	s_cbranch_execz .LBB0_2114
